# P0 prologue: the 16 serial beta/decay projection iterations per row replaced by pipelined LDS reads + one transposing DPP reduction tree + two cross-row exchanges
# speedup vs baseline: 1.2269x; 1.0153x over previous
.LBB0_248:
	s_or_b64 exec, exec, s[6:7]
	s_cmpk_lt_i32 s3, 0x4400
	v_lshlrev_b32_e32 v38, 4, v36
	v_cmp_eq_u32_e64 s[4:5], 0, v36
	s_waitcnt lgkmcnt(0)
	s_barrier
	s_cbranch_scc0 .LBB0_259
	s_add_i32 s6, s3, 0xffffc000
	s_ashr_i32 s7, s3, 31
	s_cmpk_lt_i32 s3, 0x4000
	v_readlane_b32 s36, v245, 6
	s_cselect_b32 s7, s7, 0
	s_cselect_b32 s6, s3, s6
	v_readlane_b32 s37, v245, 7
	v_readlane_b32 s38, v245, 8
	v_readlane_b32 s39, v245, 9
	s_cselect_b32 s8, s37, s39
	s_cselect_b32 s9, s36, s38
	s_lshl_b64 s[6:7], s[6:7], 12
	s_add_u32 s6, s9, s6
	s_addc_u32 s7, s8, s7
	global_load_dwordx4 v[18:21], v38, s[6:7] offset:3072 nt
	global_load_dwordx4 v[22:25], v38, s[6:7] offset:2048 nt
	global_load_dwordx4 v[26:29], v38, s[6:7] offset:1024 nt
	global_load_dwordx4 v[30:33], v38, s[6:7] nt
	v_mov_b32_e32 v41, 0
	v_lshlrev_b32_e32 v40, 2, v36
	s_mov_b64 s[8:9], 0x140000
	v_lshl_add_u64 v[2:3], s[94:95], 0, v[40:41]
	v_mov_b32_e32 v35, v41
	v_lshl_add_u64 v[42:43], v[2:3], 0, s[8:9]
	v_add_u32_e32 v1, 0, v38
	v_cmp_gt_u32_e64 s[6:7], 16, v36
	v_lshlrev_b32_e32 v37, 12, v36
	s_mov_b32 s98, 0xaaaaaaaa
	s_mov_b32 s99, 0xaaaaaaaa
	s_mov_b32 s100, 0xcccccccc
	s_mov_b32 s101, 0xcccccccc
	v_lshlrev_b32_e32 v206, 2, v36
	v_xor_b32_e32 v207, 0x80, v206
	v_xor_b32_e32 v206, 64, v206
	v_lshlrev_b32_e32 v39, 4, v36
	v_mov_b32_e32 v46, 0x358637bd
	v_mov_b32_e32 v47, 0x260
	v_mov_b32_e32 v48, 0x3a800000
	s_mov_b32 s12, s3
	v_lshl_add_u64 v[44:45], s[70:71], 0, v[34:35]
	v_readlane_b32 s40, v245, 10
	v_readlane_b32 s41, v245, 11
	v_readlane_b32 s42, v245, 12
	v_readlane_b32 s43, v245, 13
	v_readlane_b32 s44, v245, 14
	v_readlane_b32 s45, v245, 15
	v_readlane_b32 s46, v245, 16
	v_readlane_b32 s47, v245, 17
	v_readlane_b32 s48, v245, 18
	v_readlane_b32 s49, v245, 19
	v_readlane_b32 s50, v245, 20
	v_readlane_b32 s51, v245, 21
	s_waitcnt vmcnt(3)
	v_mov_b64_e32 v[2:3], v[18:19]
	s_waitcnt vmcnt(2)
	v_mov_b64_e32 v[6:7], v[22:23]
	s_waitcnt vmcnt(1)
	v_mov_b64_e32 v[10:11], v[26:27]
	s_waitcnt vmcnt(0)
	v_mov_b64_e32 v[14:15], v[30:31]
	v_mov_b64_e32 v[4:5], v[20:21]
	v_mov_b64_e32 v[8:9], v[24:25]
	v_mov_b64_e32 v[12:13], v[28:29]
	v_mov_b64_e32 v[16:17], v[32:33]
	s_branch .LBB0_251

.LBB0_253:
	v_mul_f32_e32 v35, v31, v31
	v_mul_f32_e32 v40, v33, v33
	v_fmac_f32_e32 v35, v30, v30
	v_fmac_f32_e32 v40, v32, v32
	v_add_f32_e32 v35, v35, v40
	v_mul_f32_e32 v40, v27, v27
	v_mul_f32_e32 v49, v29, v29
	v_fmac_f32_e32 v40, v26, v26
	v_fmac_f32_e32 v49, v28, v28
	v_add_f32_e32 v40, v40, v49
	v_add_f32_e32 v35, v40, v35
	v_mul_f32_e32 v40, v23, v23
	v_mul_f32_e32 v49, v25, v25
	v_fmac_f32_e32 v40, v22, v22
	v_fmac_f32_e32 v49, v24, v24
	v_add_f32_e32 v40, v40, v49
	v_add_f32_e32 v35, v40, v35
	v_mul_f32_e32 v40, v19, v19
	v_mul_f32_e32 v49, v21, v21
	v_fmac_f32_e32 v40, v18, v18
	v_fmac_f32_e32 v49, v20, v20
	v_add_f32_e32 v40, v40, v49
	v_add_f32_e32 v35, v40, v35
	v_mov_b32_e32 v40, 0
	s_ashr_i32 s13, s12, 31
	v_add_f32_dpp v35, v35, v35 row_ror:8 row_mask:0xf bank_mask:0xf bound_ctrl:1
	s_lshl_b64 s[20:21], s[12:13], 11
	v_lshl_add_u64 v[50:51], v[44:45], 0, s[20:21]
	v_add_f32_dpp v35, v35, v35 row_ror:4 row_mask:0xf bank_mask:0xf bound_ctrl:1
	v_cvt_pk_bf16_f32 v52, v30, v31
	v_cvt_pk_bf16_f32 v53, v32, v33
	v_add_f32_dpp v35, v35, v35 quad_perm:[2,3,0,1] row_mask:0xf bank_mask:0xf bound_ctrl:1
	global_store_dwordx2 v[50:51], v[52:53], off
	v_cvt_pk_bf16_f32 v52, v26, v27
	v_add_f32_dpp v35, v35, v35 quad_perm:[1,0,3,2] row_mask:0xf bank_mask:0xf bound_ctrl:1
	v_cvt_pk_bf16_f32 v53, v28, v29
	global_store_dwordx2 v[50:51], v[52:53], off offset:512
	v_mov_b32_dpp v40, v35 row_bcast:15 row_mask:0xa bank_mask:0xf
	v_add_f32_e32 v35, v35, v40
	v_mov_b32_e32 v40, 0
	v_cvt_pk_bf16_f32 v52, v22, v23
	v_cvt_pk_bf16_f32 v53, v24, v25
	v_mov_b32_dpp v40, v35 row_bcast:31 row_mask:0xc bank_mask:0xf
	v_add_f32_e32 v35, v35, v40
	global_store_dwordx2 v[50:51], v[52:53], off offset:1024
	v_readlane_b32 s8, v35, 63
	v_cvt_pk_bf16_f32 v52, v18, v19
	v_cvt_pk_bf16_f32 v53, v20, v21
	v_mov_b32_e32 v35, 0
	s_mov_b32 s9, 0
	global_store_dwordx2 v[50:51], v[52:53], off offset:1536
	ds_read_b128 v[126:129], v1 offset:0
	ds_read_b128 v[130:133], v1 offset:1024
	ds_read_b128 v[134:137], v1 offset:2048
	ds_read_b128 v[138:141], v1 offset:3072
	ds_read_b128 v[142:145], v1 offset:4096
	ds_read_b128 v[146:149], v1 offset:5120
	ds_read_b128 v[150:153], v1 offset:6144
	ds_read_b128 v[154:157], v1 offset:7168
	ds_read_b128 v[160:163], v1 offset:8192
	ds_read_b128 v[164:167], v1 offset:9216
	ds_read_b128 v[168:171], v1 offset:10240
	ds_read_b128 v[172:175], v1 offset:11264
	s_waitcnt lgkmcnt(8)
	v_mul_f32_e32 v110, v30, v126
	v_mul_f32_e32 v158, v31, v127
	v_fmac_f32_e32 v110, v32, v128
	v_fmac_f32_e32 v158, v33, v129
	v_fmac_f32_e32 v110, v26, v130
	v_fmac_f32_e32 v158, v27, v131
	v_fmac_f32_e32 v110, v28, v132
	v_fmac_f32_e32 v158, v29, v133
	v_fmac_f32_e32 v110, v22, v134
	v_fmac_f32_e32 v158, v23, v135
	v_fmac_f32_e32 v110, v24, v136
	v_fmac_f32_e32 v158, v25, v137
	v_fmac_f32_e32 v110, v18, v138
	v_fmac_f32_e32 v158, v19, v139
	v_fmac_f32_e32 v110, v20, v140
	v_fmac_f32_e32 v158, v21, v141
	ds_read_b128 v[176:179], v1 offset:12288
	ds_read_b128 v[180:183], v1 offset:13312
	ds_read_b128 v[184:187], v1 offset:14336
	ds_read_b128 v[188:191], v1 offset:15360
	v_add_f32_e32 v110, v110, v158
	s_waitcnt lgkmcnt(8)
	v_mul_f32_e32 v111, v30, v142
	v_mul_f32_e32 v158, v31, v143
	v_fmac_f32_e32 v111, v32, v144
	v_fmac_f32_e32 v158, v33, v145
	v_fmac_f32_e32 v111, v26, v146
	v_fmac_f32_e32 v158, v27, v147
	v_fmac_f32_e32 v111, v28, v148
	v_fmac_f32_e32 v158, v29, v149
	v_fmac_f32_e32 v111, v22, v150
	v_fmac_f32_e32 v158, v23, v151
	v_fmac_f32_e32 v111, v24, v152
	v_fmac_f32_e32 v158, v25, v153
	v_fmac_f32_e32 v111, v18, v154
	v_fmac_f32_e32 v158, v19, v155
	v_fmac_f32_e32 v111, v20, v156
	v_fmac_f32_e32 v158, v21, v157
	ds_read_b128 v[126:129], v1 offset:16384
	ds_read_b128 v[130:133], v1 offset:17408
	ds_read_b128 v[134:137], v1 offset:18432
	ds_read_b128 v[138:141], v1 offset:19456
	v_add_f32_e32 v111, v111, v158
	s_waitcnt lgkmcnt(8)
	v_mul_f32_e32 v112, v30, v160
	v_mul_f32_e32 v158, v31, v161
	v_fmac_f32_e32 v112, v32, v162
	v_fmac_f32_e32 v158, v33, v163
	v_fmac_f32_e32 v112, v26, v164
	v_fmac_f32_e32 v158, v27, v165
	v_fmac_f32_e32 v112, v28, v166
	v_fmac_f32_e32 v158, v29, v167
	v_fmac_f32_e32 v112, v22, v168
	v_fmac_f32_e32 v158, v23, v169
	v_fmac_f32_e32 v112, v24, v170
	v_fmac_f32_e32 v158, v25, v171
	v_fmac_f32_e32 v112, v18, v172
	v_fmac_f32_e32 v158, v19, v173
	v_fmac_f32_e32 v112, v20, v174
	v_fmac_f32_e32 v158, v21, v175
	ds_read_b128 v[142:145], v1 offset:20480
	ds_read_b128 v[146:149], v1 offset:21504
	ds_read_b128 v[150:153], v1 offset:22528
	ds_read_b128 v[154:157], v1 offset:23552
	v_add_f32_e32 v112, v112, v158
	s_waitcnt lgkmcnt(8)
	v_mul_f32_e32 v113, v30, v176
	v_mul_f32_e32 v158, v31, v177
	v_fmac_f32_e32 v113, v32, v178
	v_fmac_f32_e32 v158, v33, v179
	v_fmac_f32_e32 v113, v26, v180
	v_fmac_f32_e32 v158, v27, v181
	v_fmac_f32_e32 v113, v28, v182
	v_fmac_f32_e32 v158, v29, v183
	v_fmac_f32_e32 v113, v22, v184
	v_fmac_f32_e32 v158, v23, v185
	v_fmac_f32_e32 v113, v24, v186
	v_fmac_f32_e32 v158, v25, v187
	v_fmac_f32_e32 v113, v18, v188
	v_fmac_f32_e32 v158, v19, v189
	v_fmac_f32_e32 v113, v20, v190
	v_fmac_f32_e32 v158, v21, v191
	ds_read_b128 v[160:163], v1 offset:24576
	ds_read_b128 v[164:167], v1 offset:25600
	ds_read_b128 v[168:171], v1 offset:26624
	ds_read_b128 v[172:175], v1 offset:27648
	v_add_f32_e32 v113, v113, v158
	s_waitcnt lgkmcnt(8)
	v_mul_f32_e32 v114, v30, v126
	v_mul_f32_e32 v158, v31, v127
	v_fmac_f32_e32 v114, v32, v128
	v_fmac_f32_e32 v158, v33, v129
	v_fmac_f32_e32 v114, v26, v130
	v_fmac_f32_e32 v158, v27, v131
	v_fmac_f32_e32 v114, v28, v132
	v_fmac_f32_e32 v158, v29, v133
	v_fmac_f32_e32 v114, v22, v134
	v_fmac_f32_e32 v158, v23, v135
	v_fmac_f32_e32 v114, v24, v136
	v_fmac_f32_e32 v158, v25, v137
	v_fmac_f32_e32 v114, v18, v138
	v_fmac_f32_e32 v158, v19, v139
	v_fmac_f32_e32 v114, v20, v140
	v_fmac_f32_e32 v158, v21, v141
	ds_read_b128 v[176:179], v1 offset:28672
	ds_read_b128 v[180:183], v1 offset:29696
	ds_read_b128 v[184:187], v1 offset:30720
	ds_read_b128 v[188:191], v1 offset:31744
	v_add_f32_e32 v114, v114, v158
	s_waitcnt lgkmcnt(8)
	v_mul_f32_e32 v115, v30, v142
	v_mul_f32_e32 v158, v31, v143
	v_fmac_f32_e32 v115, v32, v144
	v_fmac_f32_e32 v158, v33, v145
	v_fmac_f32_e32 v115, v26, v146
	v_fmac_f32_e32 v158, v27, v147
	v_fmac_f32_e32 v115, v28, v148
	v_fmac_f32_e32 v158, v29, v149
	v_fmac_f32_e32 v115, v22, v150
	v_fmac_f32_e32 v158, v23, v151
	v_fmac_f32_e32 v115, v24, v152
	v_fmac_f32_e32 v158, v25, v153
	v_fmac_f32_e32 v115, v18, v154
	v_fmac_f32_e32 v158, v19, v155
	v_fmac_f32_e32 v115, v20, v156
	v_fmac_f32_e32 v158, v21, v157
	ds_read_b128 v[126:129], v1 offset:32768
	ds_read_b128 v[130:133], v1 offset:33792
	ds_read_b128 v[134:137], v1 offset:34816
	ds_read_b128 v[138:141], v1 offset:35840
	v_add_f32_e32 v115, v115, v158
	s_waitcnt lgkmcnt(8)
	v_mul_f32_e32 v116, v30, v160
	v_mul_f32_e32 v158, v31, v161
	v_fmac_f32_e32 v116, v32, v162
	v_fmac_f32_e32 v158, v33, v163
	v_fmac_f32_e32 v116, v26, v164
	v_fmac_f32_e32 v158, v27, v165
	v_fmac_f32_e32 v116, v28, v166
	v_fmac_f32_e32 v158, v29, v167
	v_fmac_f32_e32 v116, v22, v168
	v_fmac_f32_e32 v158, v23, v169
	v_fmac_f32_e32 v116, v24, v170
	v_fmac_f32_e32 v158, v25, v171
	v_fmac_f32_e32 v116, v18, v172
	v_fmac_f32_e32 v158, v19, v173
	v_fmac_f32_e32 v116, v20, v174
	v_fmac_f32_e32 v158, v21, v175
	ds_read_b128 v[142:145], v1 offset:36864
	ds_read_b128 v[146:149], v1 offset:37888
	ds_read_b128 v[150:153], v1 offset:38912
	ds_read_b128 v[154:157], v1 offset:39936
	v_add_f32_e32 v116, v116, v158
	s_waitcnt lgkmcnt(8)
	v_mul_f32_e32 v117, v30, v176
	v_mul_f32_e32 v158, v31, v177
	v_fmac_f32_e32 v117, v32, v178
	v_fmac_f32_e32 v158, v33, v179
	v_fmac_f32_e32 v117, v26, v180
	v_fmac_f32_e32 v158, v27, v181
	v_fmac_f32_e32 v117, v28, v182
	v_fmac_f32_e32 v158, v29, v183
	v_fmac_f32_e32 v117, v22, v184
	v_fmac_f32_e32 v158, v23, v185
	v_fmac_f32_e32 v117, v24, v186
	v_fmac_f32_e32 v158, v25, v187
	v_fmac_f32_e32 v117, v18, v188
	v_fmac_f32_e32 v158, v19, v189
	v_fmac_f32_e32 v117, v20, v190
	v_fmac_f32_e32 v158, v21, v191
	ds_read_b128 v[160:163], v1 offset:40960
	ds_read_b128 v[164:167], v1 offset:41984
	ds_read_b128 v[168:171], v1 offset:43008
	ds_read_b128 v[172:175], v1 offset:44032
	v_add_f32_e32 v117, v117, v158
	s_waitcnt lgkmcnt(8)
	v_mul_f32_e32 v118, v30, v126
	v_mul_f32_e32 v158, v31, v127
	v_fmac_f32_e32 v118, v32, v128
	v_fmac_f32_e32 v158, v33, v129
	v_fmac_f32_e32 v118, v26, v130
	v_fmac_f32_e32 v158, v27, v131
	v_fmac_f32_e32 v118, v28, v132
	v_fmac_f32_e32 v158, v29, v133
	v_fmac_f32_e32 v118, v22, v134
	v_fmac_f32_e32 v158, v23, v135
	v_fmac_f32_e32 v118, v24, v136
	v_fmac_f32_e32 v158, v25, v137
	v_fmac_f32_e32 v118, v18, v138
	v_fmac_f32_e32 v158, v19, v139
	v_fmac_f32_e32 v118, v20, v140
	v_fmac_f32_e32 v158, v21, v141
	ds_read_b128 v[176:179], v1 offset:45056
	ds_read_b128 v[180:183], v1 offset:46080
	ds_read_b128 v[184:187], v1 offset:47104
	ds_read_b128 v[188:191], v1 offset:48128
	v_add_f32_e32 v118, v118, v158
	s_waitcnt lgkmcnt(8)
	v_mul_f32_e32 v119, v30, v142
	v_mul_f32_e32 v158, v31, v143
	v_fmac_f32_e32 v119, v32, v144
	v_fmac_f32_e32 v158, v33, v145
	v_fmac_f32_e32 v119, v26, v146
	v_fmac_f32_e32 v158, v27, v147
	v_fmac_f32_e32 v119, v28, v148
	v_fmac_f32_e32 v158, v29, v149
	v_fmac_f32_e32 v119, v22, v150
	v_fmac_f32_e32 v158, v23, v151
	v_fmac_f32_e32 v119, v24, v152
	v_fmac_f32_e32 v158, v25, v153
	v_fmac_f32_e32 v119, v18, v154
	v_fmac_f32_e32 v158, v19, v155
	v_fmac_f32_e32 v119, v20, v156
	v_fmac_f32_e32 v158, v21, v157
	ds_read_b128 v[126:129], v1 offset:49152
	ds_read_b128 v[130:133], v1 offset:50176
	ds_read_b128 v[134:137], v1 offset:51200
	ds_read_b128 v[138:141], v1 offset:52224
	v_add_f32_e32 v119, v119, v158
	s_waitcnt lgkmcnt(8)
	v_mul_f32_e32 v120, v30, v160
	v_mul_f32_e32 v158, v31, v161
	v_fmac_f32_e32 v120, v32, v162
	v_fmac_f32_e32 v158, v33, v163
	v_fmac_f32_e32 v120, v26, v164
	v_fmac_f32_e32 v158, v27, v165
	v_fmac_f32_e32 v120, v28, v166
	v_fmac_f32_e32 v158, v29, v167
	v_fmac_f32_e32 v120, v22, v168
	v_fmac_f32_e32 v158, v23, v169
	v_fmac_f32_e32 v120, v24, v170
	v_fmac_f32_e32 v158, v25, v171
	v_fmac_f32_e32 v120, v18, v172
	v_fmac_f32_e32 v158, v19, v173
	v_fmac_f32_e32 v120, v20, v174
	v_fmac_f32_e32 v158, v21, v175
	ds_read_b128 v[142:145], v1 offset:53248
	ds_read_b128 v[146:149], v1 offset:54272
	ds_read_b128 v[150:153], v1 offset:55296
	ds_read_b128 v[154:157], v1 offset:56320
	v_add_f32_e32 v120, v120, v158
	s_waitcnt lgkmcnt(8)
	v_mul_f32_e32 v121, v30, v176
	v_mul_f32_e32 v158, v31, v177
	v_fmac_f32_e32 v121, v32, v178
	v_fmac_f32_e32 v158, v33, v179
	v_fmac_f32_e32 v121, v26, v180
	v_fmac_f32_e32 v158, v27, v181
	v_fmac_f32_e32 v121, v28, v182
	v_fmac_f32_e32 v158, v29, v183
	v_fmac_f32_e32 v121, v22, v184
	v_fmac_f32_e32 v158, v23, v185
	v_fmac_f32_e32 v121, v24, v186
	v_fmac_f32_e32 v158, v25, v187
	v_fmac_f32_e32 v121, v18, v188
	v_fmac_f32_e32 v158, v19, v189
	v_fmac_f32_e32 v121, v20, v190
	v_fmac_f32_e32 v158, v21, v191
	ds_read_b128 v[160:163], v1 offset:57344
	ds_read_b128 v[164:167], v1 offset:58368
	ds_read_b128 v[168:171], v1 offset:59392
	ds_read_b128 v[172:175], v1 offset:60416
	v_add_f32_e32 v121, v121, v158
	s_waitcnt lgkmcnt(8)
	v_mul_f32_e32 v122, v30, v126
	v_mul_f32_e32 v158, v31, v127
	v_fmac_f32_e32 v122, v32, v128
	v_fmac_f32_e32 v158, v33, v129
	v_fmac_f32_e32 v122, v26, v130
	v_fmac_f32_e32 v158, v27, v131
	v_fmac_f32_e32 v122, v28, v132
	v_fmac_f32_e32 v158, v29, v133
	v_fmac_f32_e32 v122, v22, v134
	v_fmac_f32_e32 v158, v23, v135
	v_fmac_f32_e32 v122, v24, v136
	v_fmac_f32_e32 v158, v25, v137
	v_fmac_f32_e32 v122, v18, v138
	v_fmac_f32_e32 v158, v19, v139
	v_fmac_f32_e32 v122, v20, v140
	v_fmac_f32_e32 v158, v21, v141
	ds_read_b128 v[176:179], v1 offset:61440
	ds_read_b128 v[180:183], v1 offset:62464
	ds_read_b128 v[184:187], v1 offset:63488
	ds_read_b128 v[188:191], v1 offset:64512
	v_add_f32_e32 v122, v122, v158
	s_waitcnt lgkmcnt(8)
	v_mul_f32_e32 v123, v30, v142
	v_mul_f32_e32 v158, v31, v143
	v_fmac_f32_e32 v123, v32, v144
	v_fmac_f32_e32 v158, v33, v145
	v_fmac_f32_e32 v123, v26, v146
	v_fmac_f32_e32 v158, v27, v147
	v_fmac_f32_e32 v123, v28, v148
	v_fmac_f32_e32 v158, v29, v149
	v_fmac_f32_e32 v123, v22, v150
	v_fmac_f32_e32 v158, v23, v151
	v_fmac_f32_e32 v123, v24, v152
	v_fmac_f32_e32 v158, v25, v153
	v_fmac_f32_e32 v123, v18, v154
	v_fmac_f32_e32 v158, v19, v155
	v_fmac_f32_e32 v123, v20, v156
	v_fmac_f32_e32 v158, v21, v157
	v_add_f32_e32 v123, v123, v158
	s_waitcnt lgkmcnt(4)
	v_mul_f32_e32 v124, v30, v160
	v_mul_f32_e32 v158, v31, v161
	v_fmac_f32_e32 v124, v32, v162
	v_fmac_f32_e32 v158, v33, v163
	v_fmac_f32_e32 v124, v26, v164
	v_fmac_f32_e32 v158, v27, v165
	v_fmac_f32_e32 v124, v28, v166
	v_fmac_f32_e32 v158, v29, v167
	v_fmac_f32_e32 v124, v22, v168
	v_fmac_f32_e32 v158, v23, v169
	v_fmac_f32_e32 v124, v24, v170
	v_fmac_f32_e32 v158, v25, v171
	v_fmac_f32_e32 v124, v18, v172
	v_fmac_f32_e32 v158, v19, v173
	v_fmac_f32_e32 v124, v20, v174
	v_fmac_f32_e32 v158, v21, v175
	v_add_f32_e32 v124, v124, v158
	s_waitcnt lgkmcnt(0)
	v_mul_f32_e32 v125, v30, v176
	v_mul_f32_e32 v158, v31, v177
	v_fmac_f32_e32 v125, v32, v178
	v_fmac_f32_e32 v158, v33, v179
	v_fmac_f32_e32 v125, v26, v180
	v_fmac_f32_e32 v158, v27, v181
	v_fmac_f32_e32 v125, v28, v182
	v_fmac_f32_e32 v158, v29, v183
	v_fmac_f32_e32 v125, v22, v184
	v_fmac_f32_e32 v158, v23, v185
	v_fmac_f32_e32 v125, v24, v186
	v_fmac_f32_e32 v158, v25, v187
	v_fmac_f32_e32 v125, v18, v188
	v_fmac_f32_e32 v158, v19, v189
	v_fmac_f32_e32 v125, v20, v190
	v_fmac_f32_e32 v158, v21, v191
	v_add_f32_e32 v125, v125, v158
	v_add_f32_dpp v192, v110, v110 row_ror:8 row_mask:0xf bank_mask:0xf
	v_add_f32_dpp v193, v111, v111 row_ror:8 row_mask:0xf bank_mask:0xf
	v_add_f32_dpp v194, v112, v112 row_ror:8 row_mask:0xf bank_mask:0xf
	v_add_f32_dpp v195, v113, v113 row_ror:8 row_mask:0xf bank_mask:0xf
	v_add_f32_dpp v196, v114, v114 row_ror:8 row_mask:0xf bank_mask:0xf
	v_add_f32_dpp v197, v115, v115 row_ror:8 row_mask:0xf bank_mask:0xf
	v_add_f32_dpp v198, v116, v116 row_ror:8 row_mask:0xf bank_mask:0xf
	v_add_f32_dpp v199, v117, v117 row_ror:8 row_mask:0xf bank_mask:0xf
	v_add_f32_dpp v192, v118, v118 row_ror:8 row_mask:0xf bank_mask:0xc
	v_add_f32_dpp v193, v119, v119 row_ror:8 row_mask:0xf bank_mask:0xc
	v_add_f32_dpp v194, v120, v120 row_ror:8 row_mask:0xf bank_mask:0xc
	v_add_f32_dpp v195, v121, v121 row_ror:8 row_mask:0xf bank_mask:0xc
	v_add_f32_dpp v196, v122, v122 row_ror:8 row_mask:0xf bank_mask:0xc
	v_add_f32_dpp v197, v123, v123 row_ror:8 row_mask:0xf bank_mask:0xc
	v_add_f32_dpp v198, v124, v124 row_ror:8 row_mask:0xf bank_mask:0xc
	v_add_f32_dpp v199, v125, v125 row_ror:8 row_mask:0xf bank_mask:0xc
	v_add_f32_dpp v200, v192, v192 row_half_mirror row_mask:0xf bank_mask:0x5
	v_add_f32_dpp v201, v193, v193 row_half_mirror row_mask:0xf bank_mask:0x5
	v_add_f32_dpp v202, v194, v194 row_half_mirror row_mask:0xf bank_mask:0x5
	v_add_f32_dpp v203, v195, v195 row_half_mirror row_mask:0xf bank_mask:0x5
	v_add_f32_dpp v200, v196, v196 row_half_mirror row_mask:0xf bank_mask:0xa
	v_add_f32_dpp v201, v197, v197 row_half_mirror row_mask:0xf bank_mask:0xa
	v_add_f32_dpp v202, v198, v198 row_half_mirror row_mask:0xf bank_mask:0xa
	v_add_f32_dpp v203, v199, v199 row_half_mirror row_mask:0xf bank_mask:0xa
	v_add_f32_dpp v192, v200, v200 quad_perm:[2,3,0,1] row_mask:0xf bank_mask:0xf
	v_add_f32_dpp v193, v202, v202 quad_perm:[2,3,0,1] row_mask:0xf bank_mask:0xf
	v_add_f32_dpp v194, v201, v201 quad_perm:[2,3,0,1] row_mask:0xf bank_mask:0xf
	v_add_f32_dpp v195, v203, v203 quad_perm:[2,3,0,1] row_mask:0xf bank_mask:0xf
	v_cndmask_b32_e64 v196, v192, v193, s[100:101]
	v_cndmask_b32_e64 v197, v194, v195, s[100:101]
	s_nop 0
	v_add_f32_dpp v198, v196, v196 quad_perm:[1,0,3,2] row_mask:0xf bank_mask:0xf
	v_add_f32_dpp v199, v197, v197 quad_perm:[1,0,3,2] row_mask:0xf bank_mask:0xf
	s_nop 0
	v_cndmask_b32_e64 v198, v198, v199, s[98:99]
	ds_bpermute_b32 v199, v206, v198
	s_waitcnt lgkmcnt(0)
	v_add_f32_e32 v198, v198, v199
	ds_bpermute_b32 v199, v207, v198
	s_waitcnt lgkmcnt(0)
	v_add_f32_e32 v35, v198, v199
	v_fma_f32 v18, s8, v48, v46
	s_mov_b32 s8, 0xf800000
	v_mul_f32_e32 v19, 0x4f800000, v18
	v_cmp_gt_f32_e32 vcc, s8, v18
	s_nop 1
	v_cndmask_b32_e32 v18, v18, v19, vcc
	v_sqrt_f32_e32 v19, v18
	s_nop 0
	v_add_u32_e32 v20, -1, v19
	v_add_u32_e32 v21, 1, v19
	v_fma_f32 v22, -v20, v19, v18
	v_fma_f32 v23, -v21, v19, v18
	v_cmp_ge_f32_e64 s[8:9], 0, v22
	s_nop 1
	v_cndmask_b32_e64 v19, v19, v20, s[8:9]
	v_cmp_lt_f32_e64 s[8:9], 0, v23
	s_nop 1
	v_cndmask_b32_e64 v19, v19, v21, s[8:9]
	v_mul_f32_e32 v20, 0x37800000, v19
	v_cndmask_b32_e32 v19, v19, v20, vcc
	v_cmp_class_f32_e32 vcc, v18, v47
	s_nop 1
	v_cndmask_b32_e32 v18, v19, v18, vcc
	v_div_scale_f32 v19, s[8:9], v18, v18, 1.0
	v_rcp_f32_e32 v20, v19
	s_nop 0
	v_fma_f32 v21, -v19, v20, 1.0
	v_fmac_f32_e32 v20, v21, v20
	v_div_scale_f32 v21, vcc, 1.0, v18, 1.0
	v_mul_f32_e32 v22, v21, v20
	v_fma_f32 v23, -v19, v22, v21
	v_fmac_f32_e32 v22, v23, v20
	v_fma_f32 v19, -v19, v22, v21
	v_div_fmas_f32 v19, v19, v20, v22
	v_div_fixup_f32 v18, v19, v18, 1.0
	s_and_saveexec_b64 s[8:9], s[6:7]
	s_cbranch_execz .LBB0_257
	s_lshl_b64 s[20:21], s[12:13], 6
	v_mul_f32_e32 v19, v18, v35
	v_lshl_add_u64 v[20:21], v[42:43], 0, s[20:21]
	global_store_dword v[20:21], v19, off
